# v9 without the s_setprio pairs around the attention MFMA segments
# speedup vs baseline: 1.0040x; 1.0040x over previous
; #define AT_BAR() do { __builtin_amdgcn_sched_barrier(0); asm volatile("s_waitcnt lgkmcnt(0)\n\ts_barrier" ::: "memory"); __builtin_amdgcn_sched_barrier(0); } while (0)
; #define AT_PIN_M() asm volatile("" : "+v"(p[0]), "+v"(p[1]), "+v"(o[0][0]), "+v"(o[0][1]), "+v"(o[1][0]), "+v"(o[1][1]))
; __device__ __forceinline__ void attn_phase(LAS unsigned char* lds, const bf16_t* Qb, const bf16_t* Kimg, const bf16_t* Vimg, bf16_t* AB, int bid, int G, int wave_k) {
;     ...
;             AT_MSEG(b_cur, 0, (t > 0 ? b_prev : b_cur), 2);
;             AT_PIN_M();
;             AT_BAR();
;             AT_SM(t == 0);
.LBB0_963:
	ds_read_b128 v[104:107], v160
	ds_read_b128 v[108:111], v160 offset:2048
	ds_read_b128 v[120:123], v160 offset:4096
	ds_read_b128 v[124:127], v160 offset:6144
	ds_read_b128 v[210:213], v160 offset:8192
	ds_read_b128 v[230:233], v160 offset:10240
	ds_read_b128 v[238:241], v128 offset:16384
	ds_read_b128 v[242:245], v128 offset:16896
	ds_read_b128 v[246:249], v128 offset:18432
	ds_read_b128 v[250:253], v128 offset:18944
	s_waitcnt lgkmcnt(9)
	v_mfma_f32_32x32x16_bf16 v[144:159], v[104:107], v[162:165], v[64:79]
	v_mfma_f32_32x32x16_bf16 v[128:143], v[104:107], v[186:189], v[80:95]
	s_waitcnt lgkmcnt(7)
	v_mfma_f32_32x32x16_bf16 v[144:159], v[108:111], v[166:169], v[144:159]
	v_mfma_f32_32x32x16_bf16 v[128:143], v[108:111], v[190:193], v[128:143]
	v_mfma_f32_32x32x16_bf16 v[144:159], v[120:123], v[170:173], v[144:159]
	v_mfma_f32_32x32x16_bf16 v[128:143], v[120:123], v[194:197], v[128:143]
	s_waitcnt lgkmcnt(4)
	v_mfma_f32_32x32x16_bf16 v[144:159], v[124:127], v[174:177], v[144:159]
	v_mfma_f32_32x32x16_bf16 v[128:143], v[124:127], v[198:201], v[128:143]
	v_mfma_f32_32x32x16_bf16 v[144:159], v[210:213], v[178:181], v[144:159]
	v_mfma_f32_32x32x16_bf16 v[128:143], v[210:213], v[202:205], v[128:143]
	v_mfma_f32_32x32x16_bf16 v[144:159], v[230:233], v[182:185], v[144:159]
	v_mfma_f32_32x32x16_bf16 v[128:143], v[230:233], v[206:209], v[128:143]
	s_waitcnt lgkmcnt(0)
	v_mfma_f32_32x32x16_bf16 v[48:63], v[238:241], v[116:119], v[48:63]
	v_mfma_f32_32x32x16_bf16 v[32:47], v[242:245], v[116:119], v[32:47]
	v_mfma_f32_32x32x16_bf16 v[16:31], v[238:241], v[100:103], v[16:31]
	v_mfma_f32_32x32x16_bf16 v[0:15], v[242:245], v[100:103], v[0:15]
	v_mfma_f32_32x32x16_bf16 v[48:63], v[246:249], v[112:115], v[48:63]
	v_mfma_f32_32x32x16_bf16 v[32:47], v[250:253], v[112:115], v[32:47]
	v_mfma_f32_32x32x16_bf16 v[16:31], v[246:249], v[96:99], v[16:31]
	v_mfma_f32_32x32x16_bf16 v[0:15], v[250:253], v[96:99], v[0:15]
	s_barrier
	s_nop 1
	v_exp_f32_e32 v144, v144
	v_exp_f32_e32 v145, v145
	v_exp_f32_e32 v146, v146
	v_exp_f32_e32 v147, v147
	v_add_f32_e32 v210, v144, v145
	v_exp_f32_e32 v148, v148
	v_add_f32_e32 v210, v210, v146
	v_exp_f32_e32 v149, v149
	v_add_f32_e32 v210, v210, v147
	v_exp_f32_e32 v150, v150
	v_add_f32_e32 v210, v210, v148
	v_exp_f32_e32 v151, v151
	v_add_f32_e32 v210, v210, v149
	v_exp_f32_e32 v152, v152
	v_add_f32_e32 v210, v210, v150
	v_exp_f32_e32 v153, v153
	v_add_f32_e32 v210, v210, v151
	v_exp_f32_e32 v154, v154
	v_add_f32_e32 v210, v210, v152
	v_exp_f32_e32 v155, v155
	v_add_f32_e32 v210, v210, v153
	v_exp_f32_e32 v156, v156
	v_add_f32_e32 v210, v210, v154
	v_exp_f32_e32 v157, v157
	v_add_f32_e32 v210, v210, v155
	v_exp_f32_e32 v158, v158
	v_add_f32_e32 v210, v210, v156
	v_exp_f32_e32 v159, v159
	v_add_f32_e32 v210, v210, v157
	v_add_f32_e32 v210, v210, v158
	v_add_f32_e32 v210, v210, v159
	v_exp_f32_e32 v128, v128
	v_exp_f32_e32 v129, v129
	v_exp_f32_e32 v130, v130
	v_exp_f32_e32 v131, v131
	v_add_f32_e32 v211, v128, v129
	v_exp_f32_e32 v132, v132
	v_add_f32_e32 v211, v211, v130
	v_exp_f32_e32 v133, v133
	v_add_f32_e32 v211, v211, v131
	v_exp_f32_e32 v134, v134
	v_add_f32_e32 v211, v211, v132
	v_exp_f32_e32 v135, v135
	v_add_f32_e32 v211, v211, v133
	v_exp_f32_e32 v136, v136
	v_add_f32_e32 v211, v211, v134
	v_exp_f32_e32 v137, v137
	v_add_f32_e32 v211, v211, v135
	v_exp_f32_e32 v138, v138
	v_add_f32_e32 v211, v211, v136
	v_exp_f32_e32 v139, v139
	v_add_f32_e32 v211, v211, v137
	v_exp_f32_e32 v140, v140
	v_add_f32_e32 v211, v211, v138
	v_exp_f32_e32 v141, v141
	v_add_f32_e32 v211, v211, v139
	v_exp_f32_e32 v142, v142
	v_add_f32_e32 v211, v211, v140
	v_exp_f32_e32 v143, v143
	v_add_f32_e32 v211, v211, v141
	v_add_f32_e32 v211, v211, v142
	v_add_f32_e32 v211, v211, v143
	v_max_f32_e32 v212, v210, v211
	v_cmp_lt_f32_e32 vcc, 0x43800000, v212
	s_cbranch_vccnz .Lph_rare_a

; __device__ __forceinline__ void attn_phase(LAS unsigned char* lds, const bf16_t* Qb, const bf16_t* Kimg, const bf16_t* Vimg, bf16_t* AB, int bid, int G, int wave_k) {
;     ...
;             AT_MSEG(b_cur, 1, b_cur, 0);
.LBB0_969:
	ds_read_b128 v[136:139], v160 offset:512
	ds_read_b128 v[140:143], v160 offset:2560
	ds_read_b128 v[154:157], v160 offset:4608
	ds_read_b128 v[210:213], v160 offset:6656
	ds_read_b128 v[222:225], v160 offset:8704
	ds_read_b128 v[230:233], v160 offset:10752
	ds_read_b128 v[238:241], v160 offset:12288
	ds_read_b128 v[242:245], v160 offset:12800
	ds_read_b128 v[246:249], v160 offset:14336
	ds_read_b128 v[250:253], v160 offset:14848
	s_waitcnt lgkmcnt(9)
	v_mfma_f32_32x32x16_bf16 v[112:127], v[136:139], v[162:165], v[64:79]
	v_mfma_f32_32x32x16_bf16 v[96:111], v[136:139], v[186:189], v[80:95]
	s_waitcnt lgkmcnt(7)
	v_mfma_f32_32x32x16_bf16 v[112:127], v[140:143], v[166:169], v[112:127]
	v_mfma_f32_32x32x16_bf16 v[96:111], v[140:143], v[190:193], v[96:111]
	v_mfma_f32_32x32x16_bf16 v[112:127], v[154:157], v[170:173], v[112:127]
	v_mfma_f32_32x32x16_bf16 v[96:111], v[154:157], v[194:197], v[96:111]
	s_waitcnt lgkmcnt(4)
	v_mfma_f32_32x32x16_bf16 v[112:127], v[210:213], v[174:177], v[112:127]
	v_mfma_f32_32x32x16_bf16 v[96:111], v[210:213], v[198:201], v[96:111]
	v_mfma_f32_32x32x16_bf16 v[112:127], v[222:225], v[178:181], v[112:127]
	v_mfma_f32_32x32x16_bf16 v[96:111], v[222:225], v[202:205], v[96:111]
	v_mfma_f32_32x32x16_bf16 v[112:127], v[230:233], v[182:185], v[112:127]
	v_mfma_f32_32x32x16_bf16 v[96:111], v[230:233], v[206:209], v[96:111]
	s_waitcnt lgkmcnt(0)
	v_mfma_f32_32x32x16_bf16 v[48:63], v[238:241], v[148:151], v[48:63]
	v_mfma_f32_32x32x16_bf16 v[32:47], v[242:245], v[148:151], v[32:47]
	v_mfma_f32_32x32x16_bf16 v[16:31], v[238:241], v[132:135], v[16:31]
	v_mfma_f32_32x32x16_bf16 v[0:15], v[242:245], v[132:135], v[0:15]
	v_mfma_f32_32x32x16_bf16 v[48:63], v[246:249], v[144:147], v[48:63]
	v_mfma_f32_32x32x16_bf16 v[32:47], v[250:253], v[144:147], v[32:47]
	v_mfma_f32_32x32x16_bf16 v[16:31], v[246:249], v[128:131], v[16:31]
	v_mfma_f32_32x32x16_bf16 v[0:15], v[250:253], v[128:131], v[0:15]
